# v65 plus one static s_setprio 1 for waves 0-3 through each GEMM phase (waves 4-7 at 0, no per-phase flips)
# speedup vs baseline: 1.0025x; 1.0025x over previous
.LBB0_246:
	s_ashr_i32 s52, s46, 31
	s_ashr_i32 s58, s47, 31
	s_add_u32 s0, s96, 0x8b00000
	s_addc_u32 s1, s97, 0
	s_add_u32 s88, s96, 0x31238800
	s_addc_u32 s89, s97, 0
	s_add_u32 s4, s96, 0x34238800
	s_addc_u32 s5, s97, 0
	v_writelane_b32 v252, s4, 56
	s_add_u32 s74, s96, 0x35238800
	s_addc_u32 s75, s97, 0
	v_writelane_b32 v252, s5, 57
	s_andn2_b64 vcc, exec, s[2:3]
	v_writelane_b32 v252, s56, 58
	s_nop 1
	v_writelane_b32 v252, s57, 59
	s_cbranch_vccnz .LBB0_625
	s_waitcnt vmcnt(2)
	v_ashrrev_i32_e32 v1, 31, v8
	v_lshrrev_b32_e32 v1, 26, v1
	v_add_u32_e32 v1, v8, v1
	v_ashrrev_i32_e32 v9, 6, v1
	v_bfe_i32 v1, v8, 27, 1
	v_lshlrev_b32_e32 v0, 4, v8
	v_lshrrev_b32_e32 v1, 22, v1
	v_add_u32_e32 v1, v0, v1
	v_and_b32_e32 v1, 0xfffffc00, v1
	v_sub_u32_e32 v1, v0, v1
	v_lshrrev_b32_e32 v2, 4, v1
	v_bitop3_b32 v2, v2, v1, 32 bitop3:0x6c
	v_ashrrev_i32_e32 v1, 31, v1
	v_lshrrev_b32_e32 v1, 26, v1
	v_add_u32_e32 v1, v2, v1
	v_ashrrev_i32_e32 v10, 6, v1
	v_lshlrev_b32_e32 v3, 3, v9
	s_waitcnt vmcnt(0)
	v_mul_i32_i24_e32 v4, 64, v10
	v_and_b32_e32 v3, -16, v3
	v_sub_u32_e32 v2, v2, v4
	v_mov_b32_e32 v4, 1
	v_add_u32_e32 v1, v10, v3
	v_lshlrev_b32_e32 v3, 5, v9
	v_ashrrev_i16_sdwa v2, v4, sext(v2) dst_sel:DWORD dst_unused:UNUSED_PAD src0_sel:DWORD src1_sel:BYTE_0
	v_and_b32_e32 v3, 32, v3
	v_bfe_i32 v11, v2, 0, 16
	v_and_b32_e32 v6, 3, v10
	s_mov_b32 s3, 0xfffe0
	v_add_lshl_u32 v3, v3, v11, 1
	v_add_u32_e32 v0, 0x2000, v0
	v_lshlrev_b32_e32 v2, 1, v1
	v_lshrrev_b32_e32 v5, 2, v1
	v_and_or_b32 v6, v1, s3, v6
	v_lshl_add_u32 v148, v1, 12, v3
	v_ashrrev_i32_e32 v1, 31, v0
	v_lshrrev_b32_e32 v1, 22, v1
	v_add_u32_e32 v1, v0, v1
	v_ashrrev_i32_e32 v12, 10, v1
	v_mul_i32_i24_e32 v1, 0x400, v12
	v_sub_u32_e32 v0, v0, v1
	v_and_b32_e32 v2, 24, v2
	v_and_b32_e32 v5, 4, v5
	v_lshrrev_b32_e32 v1, 4, v0
	v_or3_b32 v2, v6, v5, v2
	v_bitop3_b32 v0, v1, v0, 32 bitop3:0x6c
	v_lshl_add_u32 v150, v2, 12, v3
	v_ashrrev_i32_e32 v2, 31, v0
	v_lshrrev_b32_e32 v2, 26, v2
	v_add_u32_e32 v2, v0, v2
	v_lshlrev_b32_e32 v1, 3, v12
	v_ashrrev_i32_e32 v13, 6, v2
	v_and_b32_e32 v2, 0xc0, v2
	v_and_b32_e32 v1, -16, v1
	v_sub_u32_e32 v0, v0, v2
	s_ashr_i32 s2, s31, 6
	v_add_u32_e32 v1, v13, v1
	v_ashrrev_i16_sdwa v0, v4, sext(v0) dst_sel:DWORD dst_unused:UNUSED_PAD src0_sel:DWORD src1_sel:BYTE_0
	v_and_b32_e32 v4, 3, v13
	s_ashr_i32 s91, s90, 31
	s_ashr_i32 s83, s82, 31
	v_and_or_b32 v4, v1, s3, v4
	s_ashr_i32 s3, s31, 8
	s_lshl_b32 s33, s2, 10
	s_lshl_b64 s[4:5], s[90:91], 20
	s_lshl_b64 s[6:7], s[82:83], 20
	s_add_u32 s6, s56, s6
	v_lshlrev_b32_e32 v3, 5, v12
	v_bfe_i32 v14, v0, 0, 16
	v_lshlrev_b32_e32 v0, 1, v1
	v_lshrrev_b32_e32 v2, 2, v1
	s_addc_u32 s7, s57, s7
	s_add_i32 s44, s33, 0
	v_and_b32_e32 v3, 32, v3
	v_and_b32_e32 v0, 24, v0
	v_and_b32_e32 v2, 4, v2
	s_add_i32 m0, s44, 0x10000
	v_or3_b32 v0, v4, v2, v0
	v_add_lshl_u32 v2, v3, v14, 1
	global_load_lds_dwordx4 v150, s[6:7]
	s_add_i32 m0, s44, 0x12000
	v_lshl_add_u32 v154, v0, 12, v2
	s_add_u32 s4, s96, s4
	global_load_lds_dwordx4 v154, s[6:7]
	s_addc_u32 s5, s97, s5
	s_mov_b32 m0, s44
	s_add_i32 s45, s44, 0x2000
	v_lshl_add_u32 v152, v1, 12, v2
	global_load_lds_dwordx4 v148, s[4:5]
	s_mov_b32 m0, s45
	s_add_u32 s8, s6, 0x80000
	global_load_lds_dwordx4 v152, s[4:5]
	s_addc_u32 s9, s7, 0
	s_add_i32 m0, s44, 0x14000
	v_mov_b32_e32 v157, 0
	global_load_lds_dwordx4 v150, s[8:9]
	s_add_i32 m0, s44, 0x16000
	v_mov_b32_e32 v151, v157
	global_load_lds_dwordx4 v154, s[8:9]
	s_add_u32 s8, s4, 0x80000
	s_addc_u32 s9, s5, 0
	s_add_i32 s51, s44, 0x4000
	s_mov_b32 m0, s51
	s_add_i32 s55, s44, 0x6000
	global_load_lds_dwordx4 v148, s[8:9]
	s_mov_b32 m0, s55
	v_mov_b32_e32 v155, v157
	global_load_lds_dwordx4 v152, s[8:9]
	v_mov_b32_e32 v149, v157
	v_mov_b32_e32 v153, v157
	s_movk_i32 s56, 0x2000
	s_mov_b32 s21, 0
	v_lshl_add_u64 v[6:7], s[6:7], 0, v[150:151]
	v_lshl_add_u64 v[4:5], s[6:7], 0, v[154:155]
	v_lshl_add_u64 v[2:3], s[4:5], 0, v[148:149]
	s_setprio 1
	s_cmp_lg_u32 s3, 1
	v_lshl_add_u64 v[0:1], s[4:5], 0, v[152:153]
	s_cbranch_scc1 .LBB0_249
	s_barrier
	s_setprio 0

.LBB0_960:
	v_ashrrev_i32_e32 v1, 31, v8
	v_lshrrev_b32_e32 v1, 26, v1
	v_add_u32_e32 v1, v8, v1
	v_ashrrev_i32_e32 v9, 6, v1
	v_bfe_i32 v1, v8, 27, 1
	v_lshlrev_b32_e32 v0, 4, v8
	v_lshrrev_b32_e32 v1, 22, v1
	v_add_u32_e32 v1, v0, v1
	v_and_b32_e32 v1, 0xfffffc00, v1
	v_sub_u32_e32 v1, v0, v1
	v_lshrrev_b32_e32 v2, 4, v1
	v_bitop3_b32 v2, v2, v1, 32 bitop3:0x6c
	v_ashrrev_i32_e32 v1, 31, v1
	v_lshrrev_b32_e32 v1, 26, v1
	v_lshlrev_b32_e32 v3, 3, v9
	v_add_u32_e32 v1, v2, v1
	v_and_b32_e32 v3, -16, v3
	v_ashrrev_i32_e32 v11, 6, v1
	v_add_u32_e32 v1, v11, v3
	v_lshlrev_b32_e32 v3, 5, v9
	v_and_b32_e32 v10, 32, v3
	v_mul_i32_i24_e32 v3, 64, v11
	v_sub_u32_e32 v2, v2, v3
	v_mov_b32_e32 v3, 1
	s_ashr_i32 s4, s3, 3
	v_ashrrev_i16_sdwa v2, v3, sext(v2) dst_sel:DWORD dst_unused:UNUSED_PAD src0_sel:DWORD src1_sel:BYTE_0
	v_lshlrev_b32_e32 v4, 1, v1
	v_lshrrev_b32_e32 v5, 2, v1
	v_and_b32_e32 v6, 3, v11
	s_mov_b32 s3, 0x7fffe0
	v_bfe_i32 v12, v2, 0, 16
	v_and_b32_e32 v4, 24, v4
	v_and_b32_e32 v5, 4, v5
	v_and_or_b32 v6, v1, s3, v6
	s_movk_i32 s0, 0xe00
	v_add_u32_e32 v2, v10, v12
	v_or3_b32 v4, v6, v5, v4
	v_mul_lo_u32 v1, v1, s0
	s_waitcnt vmcnt(18)
	v_add_lshl_u32 v128, v2, v1, 1
	v_mul_u32_u24_e32 v1, 0xe00, v4
	v_add_u32_e32 v0, 0x2000, v0
	v_add_lshl_u32 v130, v1, v2, 1
	v_ashrrev_i32_e32 v1, 31, v0
	v_lshrrev_b32_e32 v1, 22, v1
	v_add_u32_e32 v1, v0, v1
	s_add_i32 s2, s2, s4
	v_ashrrev_i32_e32 v13, 10, v1
	s_ashr_i32 s4, s2, 31
	v_mul_i32_i24_e32 v1, 0x400, v13
	s_lshr_b32 s4, s4, 26
	v_sub_u32_e32 v0, v0, v1
	s_add_i32 s4, s2, s4
	v_lshrrev_b32_e32 v1, 4, v0
	s_ashr_i32 s5, s4, 6
	s_andn2_b32 s4, s4, 63
	v_bitop3_b32 v0, v1, v0, 32 bitop3:0x6c
	s_sub_i32 s4, s2, s4
	v_ashrrev_i32_e32 v2, 31, v0
	s_bfe_i32 s2, s4, 0x80000
	v_lshrrev_b32_e32 v2, 26, v2
	s_bfe_u32 s2, s2, 0x3000c
	v_lshlrev_b32_e32 v1, 3, v13
	v_add_u32_e32 v2, v0, v2
	s_add_i32 s8, s4, s2
	v_and_b32_e32 v1, -16, v1
	v_ashrrev_i32_e32 v14, 6, v2
	v_lshlrev_b32_e32 v4, 5, v13
	s_bfe_i32 s2, s8, 0x80000
	s_and_b32 s8, s8, 0xf8
	v_add_u32_e32 v1, v14, v1
	v_and_b32_e32 v15, 32, v4
	v_and_b32_e32 v4, 3, v14
	s_sext_i32_i16 s9, s2
	s_sub_i32 s4, s4, s8
	v_and_b32_e32 v2, 0xc0, v2
	v_and_or_b32 v4, v1, s3, v4
	s_ashr_i32 s3, s22, 6
	s_lshl_b32 s5, s5, 3
	s_sext_i32_i8 s4, s4
	s_ashr_i32 s8, s9, 3
	s_ashr_i32 s1, s22, 8
	v_sub_u32_e32 v0, v0, v2
	s_lshl_b32 s23, s3, 10
	s_lshr_b32 s2, s9, 3
	s_add_i32 s34, s5, s4
	s_mul_hi_i32 s9, s8, 0x1c0000
	s_mul_i32 s8, s8, 0x1c0000
	v_ashrrev_i16_sdwa v0, v3, sext(v0) dst_sel:DWORD dst_unused:UNUSED_PAD src0_sel:DWORD src1_sel:BYTE_0
	v_lshlrev_b32_e32 v2, 1, v1
	v_lshrrev_b32_e32 v3, 2, v1
	s_add_u32 s16, s68, s8
	v_bfe_i32 v16, v0, 0, 16
	v_and_b32_e32 v2, 24, v2
	v_and_b32_e32 v3, 4, v3
	s_addc_u32 s17, s69, s9
	s_add_i32 s24, s23, 0
	v_add_u32_e32 v0, v15, v16
	v_or3_b32 v2, v4, v3, v2
	v_mul_lo_u32 v1, v1, s0
	s_add_i32 m0, s24, 0x10000
	v_add_lshl_u32 v132, v0, v1, 1
	v_mul_u32_u24_e32 v1, 0xe00, v2
	s_mul_i32 s5, s34, 0x1c0000
	global_load_lds_dwordx4 v130, s[16:17]
	s_add_i32 m0, s24, 0x12000
	v_add_lshl_u32 v134, v1, v0, 1
	s_mul_hi_i32 s4, s34, 0x1c0000
	s_add_u32 s14, s92, s5
	global_load_lds_dwordx4 v134, s[16:17]
	s_addc_u32 s15, s93, s4
	s_mov_b32 m0, s24
	s_add_i32 s25, s24, 0x2000
	global_load_lds_dwordx4 v128, s[14:15]
	s_mov_b32 m0, s25
	s_add_u32 s4, s16, 0xe0000
	global_load_lds_dwordx4 v132, s[14:15]
	s_addc_u32 s5, s17, 0
	s_add_i32 m0, s24, 0x14000
	v_mov_b32_e32 v131, 0
	global_load_lds_dwordx4 v130, s[4:5]
	s_add_i32 m0, s24, 0x16000
	v_mov_b32_e32 v135, v131
	global_load_lds_dwordx4 v134, s[4:5]
	s_add_u32 s4, s14, 0xe0000
	s_addc_u32 s5, s15, 0
	s_add_i32 s26, s24, 0x4000
	s_mov_b32 m0, s26
	s_add_i32 s27, s24, 0x6000
	global_load_lds_dwordx4 v128, s[4:5]
	s_mov_b32 m0, s27
	v_mov_b32_e32 v129, v131
	global_load_lds_dwordx4 v132, s[4:5]
	v_mov_b32_e32 v133, v131
	s_mov_b32 s28, 0
	v_lshl_add_u64 v[6:7], s[16:17], 0, v[130:131]
	v_lshl_add_u64 v[4:5], s[16:17], 0, v[134:135]
	v_lshl_add_u64 v[2:3], s[14:15], 0, v[128:129]
	s_setprio 1
	s_cmp_lg_u32 s1, 1
	v_lshl_add_u64 v[0:1], s[14:15], 0, v[132:133]
	s_cbranch_scc1 .LBB0_962
	s_barrier
	s_setprio 0

.LBB0_1188:
	s_add_u32 s14, s96, 0x26fc0000
	s_addc_u32 s15, s97, 0
	s_andn2_b64 vcc, exec, s[2:3]
	s_cbranch_vccnz .LBB0_1236
	v_ashrrev_i32_e32 v1, 31, v8
	v_lshrrev_b32_e32 v1, 26, v1
	v_add_u32_e32 v1, v8, v1
	v_ashrrev_i32_e32 v9, 6, v1
	v_bfe_i32 v1, v8, 27, 1
	v_lshlrev_b32_e32 v0, 4, v8
	v_lshrrev_b32_e32 v1, 22, v1
	v_add_u32_e32 v1, v0, v1
	v_and_b32_e32 v1, 0xfffffc00, v1
	v_sub_u32_e32 v1, v0, v1
	v_lshrrev_b32_e32 v2, 4, v1
	v_bitop3_b32 v2, v2, v1, 32 bitop3:0x6c
	v_ashrrev_i32_e32 v1, 31, v1
	v_lshrrev_b32_e32 v1, 26, v1
	v_add_u32_e32 v1, v2, v1
	v_ashrrev_i32_e32 v10, 6, v1
	v_lshlrev_b32_e32 v3, 3, v9
	v_mul_i32_i24_e32 v4, 64, v10
	v_and_b32_e32 v3, -16, v3
	v_sub_u32_e32 v2, v2, v4
	v_mov_b32_e32 v4, 1
	v_add_u32_e32 v1, v10, v3
	v_lshlrev_b32_e32 v3, 5, v9
	v_ashrrev_i16_sdwa v2, v4, sext(v2) dst_sel:DWORD dst_unused:UNUSED_PAD src0_sel:DWORD src1_sel:BYTE_0
	v_and_b32_e32 v3, 32, v3
	v_bfe_i32 v11, v2, 0, 16
	v_and_b32_e32 v6, 3, v10
	s_mov_b32 s3, 0xfffe0
	v_add_lshl_u32 v3, v3, v11, 1
	v_add_u32_e32 v0, 0x2000, v0
	v_lshlrev_b32_e32 v2, 1, v1
	v_lshrrev_b32_e32 v5, 2, v1
	v_and_or_b32 v6, v1, s3, v6
	v_lshl_add_u32 v128, v1, 12, v3
	v_ashrrev_i32_e32 v1, 31, v0
	v_lshrrev_b32_e32 v1, 22, v1
	v_add_u32_e32 v1, v0, v1
	v_ashrrev_i32_e32 v12, 10, v1
	v_mul_i32_i24_e32 v1, 0x400, v12
	v_sub_u32_e32 v0, v0, v1
	v_and_b32_e32 v2, 24, v2
	v_and_b32_e32 v5, 4, v5
	v_lshrrev_b32_e32 v1, 4, v0
	v_or3_b32 v2, v6, v5, v2
	v_bitop3_b32 v0, v1, v0, 32 bitop3:0x6c
	v_lshl_add_u32 v130, v2, 12, v3
	v_ashrrev_i32_e32 v2, 31, v0
	v_lshrrev_b32_e32 v2, 26, v2
	v_add_u32_e32 v2, v0, v2
	v_lshlrev_b32_e32 v1, 3, v12
	v_ashrrev_i32_e32 v13, 6, v2
	v_and_b32_e32 v2, 0xc0, v2
	v_and_b32_e32 v1, -16, v1
	v_sub_u32_e32 v0, v0, v2
	v_add_u32_e32 v1, v13, v1
	v_ashrrev_i16_sdwa v0, v4, sext(v0) dst_sel:DWORD dst_unused:UNUSED_PAD src0_sel:DWORD src1_sel:BYTE_0
	v_and_b32_e32 v4, 3, v13
	v_and_or_b32 v4, v1, s3, v4
	s_ashr_i32 s3, s19, 6
	s_ashr_i32 s2, s19, 8
	s_lshl_b32 s33, s3, 10
	s_add_u32 s36, s96, 0x24ec0000
	s_addc_u32 s37, s97, 0
	s_ashr_i32 s17, s16, 31
	s_ashr_i32 s7, s6, 31
	s_lshl_b64 s[4:5], s[16:17], 20
	s_lshl_b64 s[8:9], s[6:7], 20
	s_add_u32 s30, s66, s8
	v_lshlrev_b32_e32 v3, 5, v12
	v_bfe_i32 v14, v0, 0, 16
	v_lshlrev_b32_e32 v0, 1, v1
	v_lshrrev_b32_e32 v2, 2, v1
	s_addc_u32 s31, s67, s9
	s_add_i32 s17, s33, 0
	v_and_b32_e32 v3, 32, v3
	v_and_b32_e32 v0, 24, v0
	v_and_b32_e32 v2, 4, v2
	s_add_i32 m0, s17, 0x10000
	v_or3_b32 v0, v4, v2, v0
	v_add_lshl_u32 v2, v3, v14, 1
	global_load_lds_dwordx4 v130, s[30:31]
	s_add_i32 m0, s17, 0x12000
	v_lshl_add_u32 v134, v0, 12, v2
	s_add_u32 s28, s36, s4
	global_load_lds_dwordx4 v134, s[30:31]
	s_addc_u32 s29, s37, s5
	s_mov_b32 m0, s17
	s_add_i32 s38, s17, 0x2000
	v_lshl_add_u32 v132, v1, 12, v2
	global_load_lds_dwordx4 v128, s[28:29]
	s_mov_b32 m0, s38
	s_add_u32 s4, s30, 0x80000
	global_load_lds_dwordx4 v132, s[28:29]
	s_addc_u32 s5, s31, 0
	s_add_i32 m0, s17, 0x14000
	v_mov_b32_e32 v131, 0
	global_load_lds_dwordx4 v130, s[4:5]
	s_add_i32 m0, s17, 0x16000
	v_mov_b32_e32 v135, v131
	global_load_lds_dwordx4 v134, s[4:5]
	s_add_u32 s4, s28, 0x80000
	s_addc_u32 s5, s29, 0
	s_add_i32 s39, s17, 0x4000
	s_mov_b32 m0, s39
	s_add_i32 s40, s17, 0x6000
	global_load_lds_dwordx4 v128, s[4:5]
	s_mov_b32 m0, s40
	v_mov_b32_e32 v129, v131
	global_load_lds_dwordx4 v132, s[4:5]
	v_mov_b32_e32 v133, v131
	s_mov_b32 s5, 0
	v_lshl_add_u64 v[6:7], s[30:31], 0, v[130:131]
	v_lshl_add_u64 v[4:5], s[30:31], 0, v[134:135]
	v_lshl_add_u64 v[2:3], s[28:29], 0, v[128:129]
	s_setprio 1
	s_cmp_lg_u32 s2, 1
	v_lshl_add_u64 v[0:1], s[28:29], 0, v[132:133]
	s_cbranch_scc1 .LBB0_1191
	s_barrier
	s_setprio 0

.LBB0_1388:
	v_ashrrev_i32_e32 v1, 31, v8
	v_lshrrev_b32_e32 v1, 26, v1
	v_add_u32_e32 v1, v8, v1
	v_ashrrev_i32_e32 v9, 6, v1
	v_bfe_i32 v1, v8, 27, 1
	v_lshlrev_b32_e32 v0, 4, v8
	v_lshrrev_b32_e32 v1, 22, v1
	v_add_u32_e32 v1, v0, v1
	v_and_b32_e32 v1, 0xfffffc00, v1
	v_sub_u32_e32 v1, v0, v1
	v_lshrrev_b32_e32 v2, 4, v1
	v_bitop3_b32 v2, v2, v1, 32 bitop3:0x6c
	v_ashrrev_i32_e32 v1, 31, v1
	v_lshrrev_b32_e32 v1, 26, v1
	v_lshlrev_b32_e32 v3, 3, v9
	v_add_u32_e32 v1, v2, v1
	v_and_b32_e32 v3, -16, v3
	v_ashrrev_i32_e32 v10, 6, v1
	v_add_u32_e32 v1, v10, v3
	v_lshlrev_b32_e32 v3, 5, v9
	v_and_b32_e32 v11, 32, v3
	v_mul_i32_i24_e32 v3, 64, v10
	v_sub_u32_e32 v2, v2, v3
	v_mov_b32_e32 v3, 1
	v_ashrrev_i16_sdwa v2, v3, sext(v2) dst_sel:DWORD dst_unused:UNUSED_PAD src0_sel:DWORD src1_sel:BYTE_0
	v_lshlrev_b32_e32 v4, 1, v1
	v_lshrrev_b32_e32 v5, 2, v1
	v_and_b32_e32 v6, 3, v10
	s_mov_b32 s5, 0x7fffe0
	v_bfe_i32 v12, v2, 0, 16
	v_and_b32_e32 v4, 24, v4
	v_and_b32_e32 v5, 4, v5
	v_and_or_b32 v6, v1, s5, v6
	s_movk_i32 s2, 0xa00
	v_add_u32_e32 v2, v11, v12
	v_or3_b32 v4, v6, v5, v4
	v_mul_lo_u32 v1, v1, s2
	v_add_lshl_u32 v128, v2, v1, 1
	v_mul_u32_u24_e32 v1, 0xa00, v4
	v_add_u32_e32 v0, 0x2000, v0
	v_add_lshl_u32 v130, v1, v2, 1
	v_ashrrev_i32_e32 v1, 31, v0
	v_lshrrev_b32_e32 v1, 22, v1
	v_add_u32_e32 v1, v0, v1
	s_add_i32 s4, s4, s6
	v_ashrrev_i32_e32 v13, 10, v1
	s_ashr_i32 s6, s4, 31
	v_mul_i32_i24_e32 v1, 0x400, v13
	s_lshr_b32 s6, s6, 26
	v_sub_u32_e32 v0, v0, v1
	s_add_i32 s6, s4, s6
	v_lshrrev_b32_e32 v1, 4, v0
	s_ashr_i32 s7, s6, 6
	s_and_b32 s6, s6, 0xffc0
	v_bitop3_b32 v0, v1, v0, 32 bitop3:0x6c
	s_sub_i32 s6, s4, s6
	v_ashrrev_i32_e32 v2, 31, v0
	s_bfe_i32 s4, s6, 0x80000
	v_lshrrev_b32_e32 v2, 26, v2
	s_bfe_u32 s4, s4, 0x3000c
	v_lshlrev_b32_e32 v1, 3, v13
	v_add_u32_e32 v2, v0, v2
	s_add_i32 s8, s6, s4
	v_and_b32_e32 v1, -16, v1
	v_ashrrev_i32_e32 v14, 6, v2
	v_lshlrev_b32_e32 v4, 5, v13
	s_bfe_i32 s4, s8, 0x80000
	s_and_b32 s8, s8, 0xf8
	v_add_u32_e32 v1, v14, v1
	v_and_b32_e32 v15, 32, v4
	v_and_b32_e32 v4, 3, v14
	s_sext_i32_i16 s9, s4
	s_sub_i32 s6, s6, s8
	v_and_b32_e32 v2, 0xc0, v2
	v_and_or_b32 v4, v1, s5, v4
	s_ashr_i32 s5, s33, 6
	s_lshl_b32 s7, s7, 3
	s_sext_i32_i8 s6, s6
	s_ashr_i32 s8, s9, 3
	s_ashr_i32 s3, s33, 8
	v_sub_u32_e32 v0, v0, v2
	s_lshl_b32 s40, s5, 10
	s_lshr_b32 s4, s9, 3
	s_add_i32 s63, s7, s6
	s_mul_hi_i32 s9, s8, 0x140000
	s_mul_i32 s8, s8, 0x140000
	v_readlane_b32 s14, v252, 32
	v_ashrrev_i16_sdwa v0, v3, sext(v0) dst_sel:DWORD dst_unused:UNUSED_PAD src0_sel:DWORD src1_sel:BYTE_0
	v_lshlrev_b32_e32 v2, 1, v1
	v_lshrrev_b32_e32 v3, 2, v1
	v_readlane_b32 s15, v252, 33
	s_add_u32 s34, s14, s8
	v_bfe_i32 v16, v0, 0, 16
	v_and_b32_e32 v2, 24, v2
	v_and_b32_e32 v3, 4, v3
	s_addc_u32 s35, s15, s9
	s_add_i32 s41, s40, 0
	v_add_u32_e32 v0, v15, v16
	v_or3_b32 v2, v4, v3, v2
	v_mul_lo_u32 v1, v1, s2
	s_add_i32 m0, s41, 0x10000
	v_add_lshl_u32 v132, v0, v1, 1
	v_mul_u32_u24_e32 v1, 0xa00, v2
	s_mul_i32 s7, s63, 0x140000
	global_load_lds_dwordx4 v130, s[34:35]
	s_add_i32 m0, s41, 0x12000
	v_add_lshl_u32 v134, v1, v0, 1
	s_mul_hi_i32 s6, s63, 0x140000
	s_add_u32 s30, s16, s7
	global_load_lds_dwordx4 v134, s[34:35]
	s_addc_u32 s31, s17, s6
	s_mov_b32 m0, s41
	s_add_i32 s42, s41, 0x2000
	global_load_lds_dwordx4 v128, s[30:31]
	s_mov_b32 m0, s42
	s_add_u32 s6, s34, 0xa0000
	global_load_lds_dwordx4 v132, s[30:31]
	s_addc_u32 s7, s35, 0
	s_add_i32 m0, s41, 0x14000
	v_mov_b32_e32 v131, 0
	global_load_lds_dwordx4 v130, s[6:7]
	s_add_i32 m0, s41, 0x16000
	v_mov_b32_e32 v135, v131
	global_load_lds_dwordx4 v134, s[6:7]
	s_add_u32 s6, s30, 0xa0000
	s_addc_u32 s7, s31, 0
	s_add_i32 s43, s41, 0x4000
	s_mov_b32 m0, s43
	s_add_i32 s44, s41, 0x6000
	global_load_lds_dwordx4 v128, s[6:7]
	s_mov_b32 m0, s44
	v_mov_b32_e32 v129, v131
	global_load_lds_dwordx4 v132, s[6:7]
	v_mov_b32_e32 v133, v131
	s_mov_b32 s45, 0
	s_mov_b32 s48, 0x10000
	v_lshl_add_u64 v[6:7], s[34:35], 0, v[130:131]
	v_lshl_add_u64 v[4:5], s[34:35], 0, v[134:135]
	v_lshl_add_u64 v[2:3], s[30:31], 0, v[128:129]
	v_lshl_add_u64 v[0:1], s[30:31], 0, v[132:133]
	s_setprio 1
	s_cmp_lg_u32 s3, 1
	s_mov_b64 s[8:9], 0xa0000
	s_cbranch_scc1 .LBB0_1390
	s_barrier
	s_setprio 0
